# v39 + RoPE in-projection epilogue: invariant bias/gain loads hoisted into dead accumulator registers, waits re-derived
# speedup vs baseline: 1.0137x; 1.0137x over previous
; __device__ __forceinline__ unsigned pk_bf16(float lo, float hi) { f32x2 v = {lo, hi}; bf16x2_t b = __builtin_convertvector(v, bf16x2_t); return __builtin_bit_cast(unsigned, b); }
;     __device__ __forceinline__ void operator()(const f32x4 (&acc)[2][2][4][2], const Unit& u, int wr, int wc, int fr, int fq) const {
;     ...
;             const bool isq = (pn == 6) || (wc < 2);
;             const int hcol = (pn == 6) ? 64 * wc : (wc < 2 ? 64 * (4 + wc) : 64 * (wc - 2));
;             bf16_t* base = qkv + (isq ? OFF_QC : OFF_KC) + hcol + 8 * fqo;
;             const int pitch = isq ? 384 : 128;
;             const float* gw = (isq ? gq : gk) + 4 * fqo;
;             const float osc = isq ? 0.125f * 1.4426950408889634f : 1.0f;
; #pragma unroll
;             for (int ai = 0; ai < 2; ++ai)
; #pragma unroll
;                 for (int m = 0; m < 4; ++m) {
;                     const int row = row0 + ai * HALF + m * 16; const int t = row & 16383;
;                     const float rv = rsqrtf(rowss[row] * (1.0f / 1024.0f) + 1e-6f);
;                     float ss = 0.f; f32x4 hv[2][2];
; #pragma unroll
;                     for (int bj = 0; bj < 2; ++bj)
; #pragma unroll
;                         for (int n = 0; n < 2; ++n) { const f32x4 v = acc[ai][bj][m][n] * rv + *(const f32x4*)(bp + bj * HALF + 4 * n); hv[bj][n] = v; ss += (v[0] * v[0] + v[1] * v[1]) + (v[2] * v[2] + v[3] * v[3]); }
;                     ss += __shfl_xor(ss, 16); ss += __shfl_xor(ss, 32);
;                     const float rinv = rsqrtf(ss * (1.0f / 64.0f) + 1e-6f) * osc;
; #pragma unroll
;                     for (int bj = 0; bj < 2; ++bj) {
;                         const int pos = bj == 0 ? (t >> 6) : (t & 63);
;                         const f32x4 c = *(const f32x4*)(ropec + pos * 16 + 4 * fqo), s = *(const f32x4*)(ropes + pos * 16 + 4 * fqo);
;                         const f32x4 x1 = hv[bj][0] * rinv * *(const f32x4*)(gw + 32 * bj), x2 = hv[bj][1] * rinv * *(const f32x4*)(gw + 32 * bj + 16);
;                         const f32x4 o1 = x1 * c - x2 * s, o2 = x2 * c + x1 * s;
;                         u32x4 w; w.x = pk_bf16(o1[0], o1[1]); w.y = pk_bf16(o1[2], o1[3]); w.z = pk_bf16(o2[0], o2[1]); w.w = pk_bf16(o2[2], o2[3]);
;                         *(u32x4*)(base + (size_t)row * pitch + 32 * bj) = w;
;                     }
.LBB0_259:
	s_ashr_i32 s0, s6, 6
	s_lshl_b32 s4, s6, 8
	s_ashr_i32 s1, s0, 31
	s_add_i32 s4, s4, s11
	s_lshl_b64 s[0:1], s[0:1], 13
	s_add_u32 s5, s79, s0
	s_addc_u32 s6, s10, s1
	s_lshl_b32 s0, s66, 8
	s_ashr_i32 s1, s0, 31
	s_lshl_b64 s[0:1], s[0:1], 2
	s_add_u32 s0, s5, s0
	v_mov_b32_e32 v244, v238
	s_addc_u32 s1, s6, s1
	s_add_u32 s0, s0, s80
	v_lshlrev_b32_e32 v164, 3, v244
	v_or_b32_e32 v162, s4, v237
	s_addc_u32 s1, s1, 0
	v_ashrrev_i32_e32 v165, 31, v164
	v_lshl_add_u64 v[166:167], v[164:165], 2, s[0:1]
	s_mov_b64 s[0:1], -1
	s_cmp_gt_i32 s66, 5
	v_ashrrev_i32_e32 v163, 31, v162
	v_or_b32_e32 v243, 16, v162
	v_or_b32_e32 v242, 32, v162
	v_or_b32_e32 v241, 48, v162
	s_cbranch_scc0 .LBB0_261
	s_cmp_eq_u32 s66, 6
	s_cselect_b64 s[0:1], -1, 0
	s_and_b64 s[6:7], s[0:1], exec
	v_readlane_b32 s5, v255, 23
	s_cselect_b32 s34, s81, s5
	s_or_b64 vcc, s[0:1], s[38:39]
	s_and_b64 s[0:1], vcc, exec
	s_mov_b32 s0, 0x5800000
	s_cselect_b32 s0, s0, 0x7000000
	s_add_u32 s5, s2, s0
	s_addc_u32 s6, s3, 0
	s_lshl_b64 s[0:1], s[34:35], 1
	s_add_u32 s0, s5, s0
	s_addc_u32 s1, s6, s1
	v_readlane_b32 s48, v252, 2
	v_lshl_add_u64 v[170:171], v[164:165], 1, s[0:1]
	s_and_b64 s[0:1], vcc, exec
	v_readlane_b32 s50, v252, 4
	v_readlane_b32 s52, v252, 6
	v_lshlrev_b32_e32 v130, 2, v244
	v_readlane_b32 s51, v252, 5
	v_readlane_b32 s53, v252, 7
	s_cselect_b32 s0, s50, s52
	v_ashrrev_i32_e32 v131, 31, v130
	s_cselect_b32 s1, s51, s53
	s_add_u32 s0, s0, s76
	v_lshlrev_b64 v[186:187], 2, v[130:131]
	v_and_b32_e32 v131, 64, v230
	s_addc_u32 s1, s1, s77
	v_xor_b32_e32 v130, 16, v230
	v_add_u32_e32 v131, 64, v131
	v_lshl_add_u64 v[168:169], s[0:1], 0, v[186:187]
	v_cmp_lt_i32_e64 s[0:1], v130, v131
	v_lshl_add_u64 v[172:173], v[162:163], 2, s[12:13]
	v_cndmask_b32_e32 v245, 1.0, v231, vcc
	v_cndmask_b32_e64 v130, v230, v130, s[0:1]
	v_lshlrev_b32_e32 v246, 2, v130
	v_xor_b32_e32 v130, 32, v230
	v_cmp_lt_i32_e64 s[0:1], v130, v131
	v_mov_b32_e32 v159, v129
	v_mov_b32_e32 v161, v129
	v_cndmask_b32_e64 v130, v230, v130, s[0:1]
	v_lshlrev_b32_e32 v247, 2, v130
	global_load_dword v130, v[172:173], off
	global_load_dword v248, v[172:173], off offset:64
	global_load_dword v249, v[172:173], off offset:128
	global_load_dword v250, v[172:173], off offset:192
	global_load_dword v251, v[172:173], off offset:512
	global_load_dword v143, v[172:173], off offset:576
	global_load_dword v145, v[172:173], off offset:640
	global_load_dword v147, v[172:173], off offset:704
	s_and_b64 s[0:1], vcc, exec
	s_movk_i32 s0, 0x180
	s_cselect_b32 s0, s0, 0x80
	s_and_b32 s1, s4, 0x3fc0
	s_add_u32 s4, s82, s1
	s_addc_u32 s5, s83, 0
	v_readlane_b32 s49, v252, 3
	v_readlane_b32 s54, v252, 8
	v_readlane_b32 s55, v252, 9
	v_readlane_b32 s56, v252, 10
	v_readlane_b32 s57, v252, 11
	v_readlane_b32 s58, v252, 12
	v_readlane_b32 s59, v252, 13
	v_readlane_b32 s60, v252, 14
	v_readlane_b32 s61, v252, 15
	v_readlane_b32 s62, v252, 16
	v_readlane_b32 s63, v252, 17
	s_waitcnt vmcnt(7)
	v_fmamk_f32 v130, v130, 0x3a800000, v227
	s_nop 0
	v_rsq_f32_e32 v130, v130
	s_nop 0
	v_mov_b32_e32 v188, v130
	global_load_dwordx4 v[130:133], v[166:167], off offset:16
	global_load_dwordx4 v[134:137], v[166:167], off
	s_waitcnt vmcnt(1)
	v_pk_fma_f32 v[140:141], v[122:123], v[188:189], v[132:133] op_sel_hi:[1,0,1]
	s_waitcnt vmcnt(0)
	v_pk_fma_f32 v[192:193], v[124:125], v[188:189], v[134:135] op_sel_hi:[1,0,1]
	v_pk_fma_f32 v[194:195], v[126:127], v[188:189], v[136:137] op_sel_hi:[1,0,1]
	v_pk_mul_f32 v[136:137], v[192:193], v[192:193]
	v_pk_mul_f32 v[134:135], v[194:195], v[194:195]
	s_nop 0
	v_pk_mov_b32 v[138:139], v[136:137], v[134:135] op_sel:[1,0]
	v_mov_b32_e32 v137, v135
	v_pk_add_f32 v[134:135], v[138:139], v[136:137]
	v_pk_fma_f32 v[138:139], v[120:121], v[188:189], v[130:131] op_sel_hi:[1,0,1]
	v_pk_mul_f32 v[130:131], v[140:141], v[140:141]
	v_pk_mul_f32 v[132:133], v[138:139], v[138:139]
	v_pk_add_f32 v[198:199], v[134:135], v[134:135] op_sel_hi:[0,1]
	v_pk_mov_b32 v[134:135], v[132:133], v[130:131] op_sel:[1,0]
	v_mov_b32_e32 v133, v131
	v_pk_add_f32 v[130:131], v[134:135], v[132:133]
	s_nop 0
	v_pk_add_f32 v[200:201], v[130:131], v[130:131] op_sel_hi:[0,1]
	global_load_dwordx4 v[130:133], v[166:167], off offset:528
	global_load_dwordx4 v[134:137], v[166:167], off offset:512
	s_waitcnt vmcnt(1)
	v_pk_fma_f32 v[190:191], v[58:59], v[188:189], v[132:133] op_sel_hi:[1,0,1]
	s_waitcnt vmcnt(0)
	v_pk_fma_f32 v[206:207], v[60:61], v[188:189], v[134:135] op_sel_hi:[1,0,1]
	v_pk_fma_f32 v[204:205], v[62:63], v[188:189], v[136:137] op_sel_hi:[1,0,1]
	v_mul_f32_e32 v134, v206, v206
	v_pk_fma_f32 v[134:135], v[206:207], v[206:207], v[134:135] op_sel_hi:[1,1,0]
	v_pk_fma_f32 v[196:197], v[56:57], v[188:189], v[130:131] op_sel_hi:[1,0,1]
	global_load_dwordx4 v[120:123], v[166:167], off offset:16
	global_load_dwordx4 v[124:127], v[166:167], off
	global_load_dwordx4 v[56:59], v[166:167], off offset:528
	global_load_dwordx4 v[60:63], v[166:167], off offset:512
	v_mul_f32_e32 v134, v204, v204
	v_pk_fma_f32 v[136:137], v[204:205], v[204:205], v[134:135] op_sel_hi:[1,1,0]
	v_mul_f32_e32 v134, v196, v196
	v_mul_f32_e32 v136, v197, v197
	v_mul_f32_e32 v198, v190, v190
	v_mul_f32_e32 v200, v191, v191
	v_pk_add_f32 v[130:131], v[134:135], v[136:137]
	v_pk_add_f32 v[132:133], v[198:199], v[200:201]
	v_lshl_add_u64 v[200:201], s[4:5], 0, v[186:187]
	v_pk_add_f32 v[130:131], v[130:131], v[132:133]
	s_add_u32 s4, s84, s1
	v_add_f32_e32 v130, v130, v131
	ds_bpermute_b32 v131, v246, v130
	s_addc_u32 s5, s85, 0
	v_lshl_add_u64 v[202:203], s[4:5], 0, v[186:187]
	global_load_dwordx4 v[134:137], v[200:201], off
	s_waitcnt lgkmcnt(0)
; __device__ __forceinline__ unsigned pk_bf16(float lo, float hi) { f32x2 v = {lo, hi}; bf16x2_t b = __builtin_convertvector(v, bf16x2_t); return __builtin_bit_cast(unsigned, b); }
;     __device__ __forceinline__ void operator()(const f32x4 (&acc)[2][2][4][2], const Unit& u, int wr, int wc, int fr, int fq) const {
;     ...
;             for (int ai = 0; ai < 2; ++ai)
; #pragma unroll
;                 for (int m = 0; m < 4; ++m) {
;                     const int row = row0 + ai * HALF + m * 16; const int t = row & 16383;
;                     const float rv = rsqrtf(rowss[row] * (1.0f / 1024.0f) + 1e-6f);
;                     float ss = 0.f; f32x4 hv[2][2];
; #pragma unroll
;                     for (int bj = 0; bj < 2; ++bj)
; #pragma unroll
;                         for (int n = 0; n < 2; ++n) { const f32x4 v = acc[ai][bj][m][n] * rv + *(const f32x4*)(bp + bj * HALF + 4 * n); hv[bj][n] = v; ss += (v[0] * v[0] + v[1] * v[1]) + (v[2] * v[2] + v[3] * v[3]); }
;                     ss += __shfl_xor(ss, 16); ss += __shfl_xor(ss, 32);
;                     const float rinv = rsqrtf(ss * (1.0f / 64.0f) + 1e-6f) * osc;
; #pragma unroll
;                     for (int bj = 0; bj < 2; ++bj) {
;                         const int pos = bj == 0 ? (t >> 6) : (t & 63);
;                         const f32x4 c = *(const f32x4*)(ropec + pos * 16 + 4 * fqo), s = *(const f32x4*)(ropes + pos * 16 + 4 * fqo);
;                         const f32x4 x1 = hv[bj][0] * rinv * *(const f32x4*)(gw + 32 * bj), x2 = hv[bj][1] * rinv * *(const f32x4*)(gw + 32 * bj + 16);
;                         const f32x4 o1 = x1 * c - x2 * s, o2 = x2 * c + x1 * s;
;                         u32x4 w; w.x = pk_bf16(o1[0], o1[1]); w.y = pk_bf16(o1[2], o1[3]); w.z = pk_bf16(o2[0], o2[1]); w.w = pk_bf16(o2[2], o2[3]);
;                         *(u32x4*)(base + (size_t)row * pitch + 32 * bj) = w;
;                     }
	v_add_f32_e32 v130, v130, v131
	ds_bpermute_b32 v131, v247, v130
	s_waitcnt lgkmcnt(0)
	v_add_f32_e32 v130, v130, v131
	v_fmamk_f32 v130, v130, 0x3c800000, v227
	s_nop 0
	v_rsq_f32_e32 v130, v130
	s_nop 0
	v_mul_f32_e32 v198, v245, v130
	v_pk_mul_f32 v[208:209], v[194:195], v[198:199] op_sel_hi:[1,0]
	v_pk_mul_f32 v[210:211], v[192:193], v[198:199] op_sel_hi:[1,0]
	global_load_dwordx4 v[192:195], v[168:169], off
	v_mad_i64_i32 v[130:131], s[6:7], s0, v162, 0
	v_lshl_add_u64 v[188:189], v[130:131], 1, v[170:171]
	global_load_dwordx4 v[130:133], v[202:203], off
	v_pk_mul_f32 v[204:205], v[204:205], v[198:199] op_sel_hi:[1,0]
	v_pk_mul_f32 v[206:207], v[206:207], v[198:199] op_sel_hi:[1,0]
	v_pk_mul_f32 v[196:197], v[196:197], v[198:199] op_sel_hi:[1,0]
	v_pk_mul_f32 v[190:191], v[190:191], v[198:199] op_sel_hi:[1,0]
	s_waitcnt vmcnt(1)
	v_pk_mul_f32 v[192:193], v[192:193], v[210:211]
	v_pk_mul_f32 v[194:195], v[194:195], v[208:209]
	v_pk_mul_f32 v[208:209], v[138:139], v[198:199] op_sel_hi:[1,0]
	v_pk_mul_f32 v[210:211], v[140:141], v[198:199] op_sel_hi:[1,0]
	global_load_dwordx4 v[138:141], v[168:169], off offset:64
	s_waitcnt vmcnt(0)
	v_pk_mul_f32 v[140:141], v[140:141], v[210:211]
	v_pk_mul_f32 v[138:139], v[138:139], v[208:209]
	v_pk_mul_f32 v[210:211], v[132:133], v[140:141]
	v_pk_mul_f32 v[208:209], v[130:131], v[138:139]
	v_pk_fma_f32 v[210:211], v[136:137], v[194:195], v[210:211] neg_lo:[0,0,1] neg_hi:[0,0,1]
	v_pk_fma_f32 v[208:209], v[134:135], v[192:193], v[208:209] neg_lo:[0,0,1] neg_hi:[0,0,1]
	v_pk_mul_f32 v[134:135], v[134:135], v[138:139]
	v_pk_mul_f32 v[136:137], v[136:137], v[140:141]
	s_nop 0
	v_pk_fma_f32 v[136:137], v[132:133], v[194:195], v[136:137]
	v_pk_fma_f32 v[132:133], v[130:131], v[192:193], v[134:135]
	v_cvt_pk_bf16_f32 v130, v208, v209
	v_cvt_pk_bf16_f32 v131, v210, v211
	v_cvt_pk_bf16_f32 v132, v132, v133
	v_cvt_pk_bf16_f32 v133, v136, v137
	global_store_dwordx4 v[188:189], v[130:133], off
	global_load_dwordx4 v[138:141], v[168:169], off offset:128
	v_lshl_add_u64 v[192:193], v[150:151], 0, v[186:187]
	v_lshl_add_u64 v[194:195], v[152:153], 0, v[186:187]
	global_load_dwordx4 v[130:133], v[192:193], off
	global_load_dwordx4 v[134:137], v[194:195], off
	s_waitcnt vmcnt(2)
	v_pk_mul_f32 v[206:207], v[138:139], v[206:207]
	v_pk_mul_f32 v[204:205], v[140:141], v[204:205]
	global_load_dwordx4 v[138:141], v[168:169], off offset:192
	s_waitcnt vmcnt(0)
	v_pk_mul_f32 v[140:141], v[140:141], v[190:191]
	v_pk_mul_f32 v[138:139], v[138:139], v[196:197]
	v_pk_mul_f32 v[196:197], v[136:137], v[140:141]
	v_pk_mul_f32 v[190:191], v[134:135], v[138:139]
	v_pk_fma_f32 v[196:197], v[132:133], v[204:205], v[196:197] neg_lo:[0,0,1] neg_hi:[0,0,1]
	v_pk_fma_f32 v[190:191], v[130:131], v[206:207], v[190:191] neg_lo:[0,0,1] neg_hi:[0,0,1]
	v_pk_mul_f32 v[130:131], v[130:131], v[138:139]
	v_pk_mul_f32 v[132:133], v[132:133], v[140:141]
	s_nop 0
	v_pk_fma_f32 v[136:137], v[136:137], v[204:205], v[132:133]
	v_pk_fma_f32 v[132:133], v[134:135], v[206:207], v[130:131]
	v_cvt_pk_bf16_f32 v130, v190, v191
	v_cvt_pk_bf16_f32 v131, v196, v197
	v_cvt_pk_bf16_f32 v132, v132, v133
	v_cvt_pk_bf16_f32 v133, v136, v137
	global_store_dwordx4 v[188:189], v[130:133], off offset:64
	s_nop 1
	v_fmamk_f32 v130, v248, 0x3a800000, v227
	s_nop 0
	v_rsq_f32_e32 v130, v130
	s_nop 0
	v_mov_b32_e32 v188, v130
	v_pk_fma_f32 v[130:131], v[112:113], v[188:189], v[120:121] op_sel_hi:[1,0,1]
	v_pk_fma_f32 v[190:191], v[116:117], v[188:189], v[124:125] op_sel_hi:[1,0,1]
	v_pk_fma_f32 v[212:213], v[118:119], v[188:189], v[126:127] op_sel_hi:[1,0,1]
	v_pk_mul_f32 v[136:137], v[190:191], v[190:191]
	v_pk_mul_f32 v[134:135], v[212:213], v[212:213]
	v_pk_fma_f32 v[132:133], v[114:115], v[188:189], v[122:123] op_sel_hi:[1,0,1]
	v_pk_mov_b32 v[138:139], v[136:137], v[134:135] op_sel:[1,0]
	v_mov_b32_e32 v137, v135
	v_pk_add_f32 v[134:135], v[138:139], v[136:137]
	v_pk_mul_f32 v[136:137], v[130:131], v[130:131]
	v_pk_add_f32 v[196:197], v[134:135], v[134:135] op_sel_hi:[0,1]
	v_pk_mul_f32 v[134:135], v[132:133], v[132:133]
	s_nop 0
	v_pk_mov_b32 v[138:139], v[136:137], v[134:135] op_sel:[1,0]
	v_mov_b32_e32 v137, v135
	v_pk_add_f32 v[134:135], v[138:139], v[136:137]
	s_nop 0
	v_pk_add_f32 v[206:207], v[134:135], v[134:135] op_sel_hi:[0,1]
	v_pk_fma_f32 v[198:199], v[50:51], v[188:189], v[58:59] op_sel_hi:[1,0,1]
	v_pk_fma_f32 v[210:211], v[52:53], v[188:189], v[60:61] op_sel_hi:[1,0,1]
	v_pk_fma_f32 v[208:209], v[54:55], v[188:189], v[62:63] op_sel_hi:[1,0,1]
	v_mul_f32_e32 v138, v210, v210
	v_pk_fma_f32 v[138:139], v[210:211], v[210:211], v[138:139] op_sel_hi:[1,1,0]
	v_pk_fma_f32 v[204:205], v[48:49], v[188:189], v[56:57] op_sel_hi:[1,0,1]
	global_load_dwordx4 v[112:115], v[168:169], off
	global_load_dwordx4 v[116:119], v[168:169], off offset:64
	global_load_dwordx4 v[48:51], v[168:169], off offset:128
	global_load_dwordx4 v[52:55], v[168:169], off offset:192
	v_mul_f32_e32 v138, v208, v208
	v_pk_fma_f32 v[140:141], v[208:209], v[208:209], v[138:139] op_sel_hi:[1,1,0]
	v_mul_f32_e32 v138, v204, v204
	v_mul_f32_e32 v140, v205, v205
	v_mul_f32_e32 v196, v198, v198
	v_mul_f32_e32 v206, v199, v199
	v_pk_add_f32 v[134:135], v[138:139], v[140:141]
	v_pk_add_f32 v[136:137], v[196:197], v[206:207]
	s_nop 0
	v_pk_add_f32 v[134:135], v[134:135], v[136:137]
	s_nop 0
	v_add_f32_e32 v134, v134, v135
	ds_bpermute_b32 v135, v246, v134
	s_waitcnt lgkmcnt(0)
	v_add_f32_e32 v134, v134, v135
	ds_bpermute_b32 v135, v247, v134
	s_waitcnt lgkmcnt(0)
; __device__ __forceinline__ unsigned pk_bf16(float lo, float hi) { f32x2 v = {lo, hi}; bf16x2_t b = __builtin_convertvector(v, bf16x2_t); return __builtin_bit_cast(unsigned, b); }
;     __device__ __forceinline__ void operator()(const f32x4 (&acc)[2][2][4][2], const Unit& u, int wr, int wc, int fr, int fq) const {
;     ...
;             for (int ai = 0; ai < 2; ++ai)
; #pragma unroll
;                 for (int m = 0; m < 4; ++m) {
;                     const int row = row0 + ai * HALF + m * 16; const int t = row & 16383;
;                     const float rv = rsqrtf(rowss[row] * (1.0f / 1024.0f) + 1e-6f);
;                     float ss = 0.f; f32x4 hv[2][2];
; #pragma unroll
;                     for (int bj = 0; bj < 2; ++bj)
; #pragma unroll
;                         for (int n = 0; n < 2; ++n) { const f32x4 v = acc[ai][bj][m][n] * rv + *(const f32x4*)(bp + bj * HALF + 4 * n); hv[bj][n] = v; ss += (v[0] * v[0] + v[1] * v[1]) + (v[2] * v[2] + v[3] * v[3]); }
;                     ss += __shfl_xor(ss, 16); ss += __shfl_xor(ss, 32);
;                     const float rinv = rsqrtf(ss * (1.0f / 64.0f) + 1e-6f) * osc;
; #pragma unroll
;                     for (int bj = 0; bj < 2; ++bj) {
;                         const int pos = bj == 0 ? (t >> 6) : (t & 63);
;                         const f32x4 c = *(const f32x4*)(ropec + pos * 16 + 4 * fqo), s = *(const f32x4*)(ropes + pos * 16 + 4 * fqo);
;                         const f32x4 x1 = hv[bj][0] * rinv * *(const f32x4*)(gw + 32 * bj), x2 = hv[bj][1] * rinv * *(const f32x4*)(gw + 32 * bj + 16);
;                         const f32x4 o1 = x1 * c - x2 * s, o2 = x2 * c + x1 * s;
;                         u32x4 w; w.x = pk_bf16(o1[0], o1[1]); w.y = pk_bf16(o1[2], o1[3]); w.z = pk_bf16(o2[0], o2[1]); w.w = pk_bf16(o2[2], o2[3]);
;                         *(u32x4*)(base + (size_t)row * pitch + 32 * bj) = w;
;                     }
	v_add_f32_e32 v134, v134, v135
	v_fmamk_f32 v134, v134, 0x3c800000, v227
	s_nop 0
	v_rsq_f32_e32 v134, v134
	s_nop 0
	v_mul_f32_e32 v206, v245, v134
	v_mad_i64_i32 v[134:135], s[4:5], s0, v243, 0
	v_lshl_add_u64 v[196:197], v[134:135], 1, v[170:171]
	global_load_dwordx4 v[134:137], v[200:201], off
	global_load_dwordx4 v[138:141], v[202:203], off
	v_pk_mul_f32 v[214:215], v[190:191], v[206:207] op_sel_hi:[1,0]
	global_load_dwordx4 v[188:191], v[168:169], off
	v_pk_mul_f32 v[212:213], v[212:213], v[206:207] op_sel_hi:[1,0]
	v_pk_mul_f32 v[198:199], v[198:199], v[206:207] op_sel_hi:[1,0]
	s_waitcnt vmcnt(0)
	v_pk_mul_f32 v[188:189], v[188:189], v[214:215]
	v_pk_mul_f32 v[190:191], v[190:191], v[212:213]
	v_pk_mul_f32 v[212:213], v[130:131], v[206:207] op_sel_hi:[1,0]
	v_pk_mul_f32 v[214:215], v[132:133], v[206:207] op_sel_hi:[1,0]
	global_load_dwordx4 v[130:133], v[168:169], off offset:64
	s_waitcnt vmcnt(0)
	v_pk_mul_f32 v[132:133], v[132:133], v[214:215]
	v_pk_mul_f32 v[130:131], v[130:131], v[212:213]
	v_pk_mul_f32 v[214:215], v[140:141], v[132:133]
	v_pk_mul_f32 v[212:213], v[138:139], v[130:131]
	v_pk_mul_f32 v[130:131], v[134:135], v[130:131]
	v_pk_mul_f32 v[132:133], v[136:137], v[132:133]
	v_pk_fma_f32 v[214:215], v[136:137], v[190:191], v[214:215] neg_lo:[0,0,1] neg_hi:[0,0,1]
	v_pk_fma_f32 v[212:213], v[134:135], v[188:189], v[212:213] neg_lo:[0,0,1] neg_hi:[0,0,1]
	v_pk_fma_f32 v[134:135], v[140:141], v[190:191], v[132:133]
	v_pk_fma_f32 v[132:133], v[138:139], v[188:189], v[130:131]
	v_cvt_pk_bf16_f32 v130, v212, v213
	v_cvt_pk_bf16_f32 v131, v214, v215
	v_cvt_pk_bf16_f32 v132, v132, v133
	v_cvt_pk_bf16_f32 v133, v134, v135
	global_store_dwordx4 v[196:197], v[130:133], off
	v_pk_mul_f32 v[212:213], v[208:209], v[206:207] op_sel_hi:[1,0]
	v_pk_mul_f32 v[214:215], v[210:211], v[206:207] op_sel_hi:[1,0]
	global_load_dwordx4 v[208:211], v[168:169], off offset:128
	v_lshl_add_u64 v[138:139], s[82:83], 0, v[186:187]
	v_lshl_add_u64 v[140:141], s[84:85], 0, v[186:187]
	v_lshl_add_u64 v[188:189], v[138:139], 0, v[128:129]
	v_lshl_add_u64 v[190:191], v[140:141], 0, v[128:129]
	global_load_dwordx4 v[134:137], v[188:189], off
	global_load_dwordx4 v[130:133], v[190:191], off
	s_waitcnt vmcnt(2)
	v_pk_mul_f32 v[210:211], v[210:211], v[212:213]
	v_pk_mul_f32 v[212:213], v[204:205], v[206:207] op_sel_hi:[1,0]
	global_load_dwordx4 v[204:207], v[168:169], off offset:192
	v_pk_mul_f32 v[208:209], v[208:209], v[214:215]
	s_waitcnt vmcnt(0)
	v_pk_mul_f32 v[198:199], v[206:207], v[198:199]
	v_pk_mul_f32 v[204:205], v[204:205], v[212:213]
	v_pk_mul_f32 v[212:213], v[132:133], v[198:199]
	v_pk_mul_f32 v[206:207], v[130:131], v[204:205]
	v_pk_fma_f32 v[212:213], v[136:137], v[210:211], v[212:213] neg_lo:[0,0,1] neg_hi:[0,0,1]
	v_pk_fma_f32 v[206:207], v[134:135], v[208:209], v[206:207] neg_lo:[0,0,1] neg_hi:[0,0,1]
	v_pk_mul_f32 v[134:135], v[134:135], v[204:205]
	v_pk_mul_f32 v[136:137], v[136:137], v[198:199]
	s_nop 0
	v_pk_fma_f32 v[136:137], v[132:133], v[210:211], v[136:137]
	v_pk_fma_f32 v[132:133], v[130:131], v[208:209], v[134:135]
	v_cvt_pk_bf16_f32 v130, v206, v207
	v_cvt_pk_bf16_f32 v131, v212, v213
	v_cvt_pk_bf16_f32 v132, v132, v133
	v_cvt_pk_bf16_f32 v133, v136, v137
	global_store_dwordx4 v[196:197], v[130:133], off offset:64
	s_nop 1
	v_fmamk_f32 v130, v249, 0x3a800000, v227
	s_nop 0
	v_rsq_f32_e32 v130, v130
	s_nop 0
	v_mov_b32_e32 v196, v130
	v_pk_fma_f32 v[216:217], v[104:105], v[196:197], v[120:121] op_sel_hi:[1,0,1]
	v_pk_fma_f32 v[198:199], v[108:109], v[196:197], v[124:125] op_sel_hi:[1,0,1]
	v_pk_fma_f32 v[220:221], v[110:111], v[196:197], v[126:127] op_sel_hi:[1,0,1]
	v_pk_mul_f32 v[136:137], v[198:199], v[198:199]
	v_pk_mul_f32 v[134:135], v[220:221], v[220:221]
	v_pk_fma_f32 v[218:219], v[106:107], v[196:197], v[122:123] op_sel_hi:[1,0,1]
	v_pk_mov_b32 v[204:205], v[136:137], v[134:135] op_sel:[1,0]
	v_mov_b32_e32 v137, v135
	v_pk_add_f32 v[134:135], v[204:205], v[136:137]
	v_pk_mul_f32 v[130:131], v[218:219], v[218:219]
	v_pk_mul_f32 v[132:133], v[216:217], v[216:217]
	v_pk_add_f32 v[204:205], v[134:135], v[134:135] op_sel_hi:[0,1]
	v_pk_mov_b32 v[134:135], v[132:133], v[130:131] op_sel:[1,0]
	v_mov_b32_e32 v133, v131
	v_pk_add_f32 v[130:131], v[134:135], v[132:133]
	s_nop 0
	v_pk_add_f32 v[210:211], v[130:131], v[130:131] op_sel_hi:[0,1]
	v_pk_fma_f32 v[206:207], v[42:43], v[196:197], v[58:59] op_sel_hi:[1,0,1]
	v_pk_fma_f32 v[214:215], v[44:45], v[196:197], v[60:61] op_sel_hi:[1,0,1]
	v_pk_fma_f32 v[212:213], v[46:47], v[196:197], v[62:63] op_sel_hi:[1,0,1]
	v_mul_f32_e32 v134, v214, v214
	v_pk_fma_f32 v[134:135], v[214:215], v[214:215], v[134:135] op_sel_hi:[1,1,0]
	v_pk_fma_f32 v[208:209], v[40:41], v[196:197], v[56:57] op_sel_hi:[1,0,1]
	v_mul_f32_e32 v134, v212, v212
	v_pk_fma_f32 v[136:137], v[212:213], v[212:213], v[134:135] op_sel_hi:[1,1,0]
	v_mul_f32_e32 v134, v208, v208
	v_mul_f32_e32 v136, v209, v209
	v_mul_f32_e32 v204, v206, v206
	v_mul_f32_e32 v210, v207, v207
	v_pk_add_f32 v[130:131], v[134:135], v[136:137]
	v_pk_add_f32 v[132:133], v[204:205], v[210:211]
	s_nop 0
	v_pk_add_f32 v[130:131], v[130:131], v[132:133]
	s_nop 0
	v_add_f32_e32 v130, v130, v131
	ds_bpermute_b32 v131, v246, v130
	s_waitcnt lgkmcnt(0)
	v_add_f32_e32 v130, v130, v131
	ds_bpermute_b32 v131, v247, v130
	s_waitcnt lgkmcnt(0)
; __device__ __forceinline__ unsigned pk_bf16(float lo, float hi) { f32x2 v = {lo, hi}; bf16x2_t b = __builtin_convertvector(v, bf16x2_t); return __builtin_bit_cast(unsigned, b); }
;     __device__ __forceinline__ void operator()(const f32x4 (&acc)[2][2][4][2], const Unit& u, int wr, int wc, int fr, int fq) const {
;     ...
;             for (int ai = 0; ai < 2; ++ai)
; #pragma unroll
;                 for (int m = 0; m < 4; ++m) {
;                     const int row = row0 + ai * HALF + m * 16; const int t = row & 16383;
;                     const float rv = rsqrtf(rowss[row] * (1.0f / 1024.0f) + 1e-6f);
;                     float ss = 0.f; f32x4 hv[2][2];
; #pragma unroll
;                     for (int bj = 0; bj < 2; ++bj)
; #pragma unroll
;                         for (int n = 0; n < 2; ++n) { const f32x4 v = acc[ai][bj][m][n] * rv + *(const f32x4*)(bp + bj * HALF + 4 * n); hv[bj][n] = v; ss += (v[0] * v[0] + v[1] * v[1]) + (v[2] * v[2] + v[3] * v[3]); }
;                     ss += __shfl_xor(ss, 16); ss += __shfl_xor(ss, 32);
;                     const float rinv = rsqrtf(ss * (1.0f / 64.0f) + 1e-6f) * osc;
; #pragma unroll
;                     for (int bj = 0; bj < 2; ++bj) {
;                         const int pos = bj == 0 ? (t >> 6) : (t & 63);
;                         const f32x4 c = *(const f32x4*)(ropec + pos * 16 + 4 * fqo), s = *(const f32x4*)(ropes + pos * 16 + 4 * fqo);
;                         const f32x4 x1 = hv[bj][0] * rinv * *(const f32x4*)(gw + 32 * bj), x2 = hv[bj][1] * rinv * *(const f32x4*)(gw + 32 * bj + 16);
;                         const f32x4 o1 = x1 * c - x2 * s, o2 = x2 * c + x1 * s;
;                         u32x4 w; w.x = pk_bf16(o1[0], o1[1]); w.y = pk_bf16(o1[2], o1[3]); w.z = pk_bf16(o2[0], o2[1]); w.w = pk_bf16(o2[2], o2[3]);
;                         *(u32x4*)(base + (size_t)row * pitch + 32 * bj) = w;
;                     }
	v_add_f32_e32 v130, v130, v131
	v_fmamk_f32 v130, v130, 0x3c800000, v227
	s_nop 0
	v_rsq_f32_e32 v130, v130
	s_nop 0
	v_mul_f32_e32 v210, v245, v130
	v_mad_i64_i32 v[130:131], s[4:5], s0, v242, 0
	v_lshl_add_u64 v[204:205], v[130:131], 1, v[170:171]
	global_load_dwordx4 v[134:137], v[200:201], off
	global_load_dwordx4 v[130:133], v[202:203], off
	v_pk_mul_f32 v[222:223], v[198:199], v[210:211] op_sel_hi:[1,0]
	v_pk_mul_f32 v[220:221], v[220:221], v[210:211] op_sel_hi:[1,0]
	v_pk_mul_f32 v[216:217], v[216:217], v[210:211] op_sel_hi:[1,0]
	v_pk_mul_f32 v[218:219], v[218:219], v[210:211] op_sel_hi:[1,0]
	v_pk_mul_f32 v[196:197], v[112:113], v[222:223]
	v_pk_mul_f32 v[198:199], v[114:115], v[220:221]
	v_pk_mul_f32 v[218:219], v[118:119], v[218:219]
	v_pk_mul_f32 v[216:217], v[116:117], v[216:217]
	s_waitcnt vmcnt(0)
	v_pk_mul_f32 v[222:223], v[132:133], v[218:219]
	v_pk_mul_f32 v[220:221], v[130:131], v[216:217]
	v_pk_fma_f32 v[222:223], v[136:137], v[198:199], v[222:223] neg_lo:[0,0,1] neg_hi:[0,0,1]
	v_pk_fma_f32 v[220:221], v[134:135], v[196:197], v[220:221] neg_lo:[0,0,1] neg_hi:[0,0,1]
	v_pk_mul_f32 v[134:135], v[134:135], v[216:217]
	v_pk_mul_f32 v[136:137], v[136:137], v[218:219]
	v_pk_mul_f32 v[216:217], v[212:213], v[210:211] op_sel_hi:[1,0]
	v_pk_fma_f32 v[136:137], v[132:133], v[198:199], v[136:137]
	v_pk_fma_f32 v[132:133], v[130:131], v[196:197], v[134:135]
	v_cvt_pk_bf16_f32 v130, v220, v221
	v_cvt_pk_bf16_f32 v131, v222, v223
	v_cvt_pk_bf16_f32 v132, v132, v133
	v_cvt_pk_bf16_f32 v133, v136, v137
	global_store_dwordx4 v[204:205], v[130:133], off
	v_pk_mul_f32 v[218:219], v[214:215], v[210:211] op_sel_hi:[1,0]
	v_lshl_add_u64 v[196:197], v[138:139], 0, v[158:159]
	v_lshl_add_u64 v[198:199], v[140:141], 0, v[158:159]
	global_load_dwordx4 v[130:133], v[196:197], off
	global_load_dwordx4 v[134:137], v[198:199], off
	v_add_u32_e32 v159, 0x80, v162
	v_pk_mul_f32 v[214:215], v[50:51], v[216:217]
	v_pk_mul_f32 v[216:217], v[208:209], v[210:211] op_sel_hi:[1,0]
	v_pk_mul_f32 v[210:211], v[206:207], v[210:211] op_sel_hi:[1,0]
	v_pk_mul_f32 v[212:213], v[48:49], v[218:219]
	v_pk_mul_f32 v[208:209], v[54:55], v[210:211]
	v_pk_mul_f32 v[206:207], v[52:53], v[216:217]
	s_waitcnt vmcnt(0)
	v_pk_mul_f32 v[216:217], v[136:137], v[208:209]
	v_pk_mul_f32 v[210:211], v[134:135], v[206:207]
	v_pk_fma_f32 v[216:217], v[132:133], v[214:215], v[216:217] neg_lo:[0,0,1] neg_hi:[0,0,1]
	v_pk_fma_f32 v[210:211], v[130:131], v[212:213], v[210:211] neg_lo:[0,0,1] neg_hi:[0,0,1]
	v_pk_mul_f32 v[130:131], v[130:131], v[206:207]
	v_pk_mul_f32 v[132:133], v[132:133], v[208:209]
	s_nop 0
	v_pk_fma_f32 v[136:137], v[136:137], v[214:215], v[132:133]
	v_pk_fma_f32 v[132:133], v[134:135], v[212:213], v[130:131]
	v_cvt_pk_bf16_f32 v130, v210, v211
	v_cvt_pk_bf16_f32 v131, v216, v217
	v_cvt_pk_bf16_f32 v132, v132, v133
	v_cvt_pk_bf16_f32 v133, v136, v137
	global_store_dwordx4 v[204:205], v[130:133], off offset:64
	s_nop 1
	v_fmamk_f32 v130, v250, 0x3a800000, v227
	s_nop 0
	v_rsq_f32_e32 v130, v130
	s_nop 0
	v_mov_b32_e32 v204, v130
	v_pk_fma_f32 v[216:217], v[96:97], v[204:205], v[120:121] op_sel_hi:[1,0,1]
	v_pk_fma_f32 v[220:221], v[100:101], v[204:205], v[124:125] op_sel_hi:[1,0,1]
	v_pk_fma_f32 v[222:223], v[102:103], v[204:205], v[126:127] op_sel_hi:[1,0,1]
	v_pk_mul_f32 v[136:137], v[220:221], v[220:221]
	v_pk_mul_f32 v[134:135], v[222:223], v[222:223]
	v_pk_fma_f32 v[218:219], v[98:99], v[204:205], v[122:123] op_sel_hi:[1,0,1]
	v_pk_mov_b32 v[206:207], v[136:137], v[134:135] op_sel:[1,0]
	v_mov_b32_e32 v137, v135
	v_pk_add_f32 v[134:135], v[206:207], v[136:137]
	v_pk_mul_f32 v[130:131], v[218:219], v[218:219]
	v_pk_mul_f32 v[132:133], v[216:217], v[216:217]
	v_pk_add_f32 v[210:211], v[134:135], v[134:135] op_sel_hi:[0,1]
	v_pk_mov_b32 v[134:135], v[132:133], v[130:131] op_sel:[1,0]
	v_mov_b32_e32 v133, v131
	v_pk_add_f32 v[130:131], v[134:135], v[132:133]
	s_nop 0
	v_pk_add_f32 v[224:225], v[130:131], v[130:131] op_sel_hi:[0,1]
	v_pk_fma_f32 v[206:207], v[34:35], v[204:205], v[58:59] op_sel_hi:[1,0,1]
	v_pk_fma_f32 v[214:215], v[36:37], v[204:205], v[60:61] op_sel_hi:[1,0,1]
	v_pk_fma_f32 v[212:213], v[38:39], v[204:205], v[62:63] op_sel_hi:[1,0,1]
	v_mul_f32_e32 v134, v214, v214
	v_pk_fma_f32 v[134:135], v[214:215], v[214:215], v[134:135] op_sel_hi:[1,1,0]
	v_pk_fma_f32 v[208:209], v[32:33], v[204:205], v[56:57] op_sel_hi:[1,0,1]
	v_mul_f32_e32 v134, v212, v212
	v_pk_fma_f32 v[136:137], v[212:213], v[212:213], v[134:135] op_sel_hi:[1,1,0]
	v_mul_f32_e32 v134, v208, v208
	v_mul_f32_e32 v136, v209, v209
	v_mul_f32_e32 v210, v206, v206
	v_mul_f32_e32 v224, v207, v207
	v_pk_add_f32 v[130:131], v[134:135], v[136:137]
	v_pk_add_f32 v[132:133], v[210:211], v[224:225]
	s_nop 0
	v_pk_add_f32 v[130:131], v[130:131], v[132:133]
	s_nop 0
	v_add_f32_e32 v130, v130, v131
	ds_bpermute_b32 v131, v246, v130
	s_waitcnt lgkmcnt(0)
	v_add_f32_e32 v130, v130, v131
	ds_bpermute_b32 v131, v247, v130
	s_waitcnt lgkmcnt(0)
	v_add_f32_e32 v130, v130, v131
	v_fmamk_f32 v130, v130, 0x3c800000, v227
	s_nop 0
	v_rsq_f32_e32 v130, v130
	s_nop 0
	v_mul_f32_e32 v210, v245, v130
	v_mad_i64_i32 v[130:131], s[4:5], s0, v241, 0
	v_lshl_add_u64 v[204:205], v[130:131], 1, v[170:171]
	global_load_dwordx4 v[134:137], v[200:201], off
	global_load_dwordx4 v[130:133], v[202:203], off
	v_pk_mul_f32 v[222:223], v[222:223], v[210:211] op_sel_hi:[1,0]
	v_pk_mul_f32 v[220:221], v[220:221], v[210:211] op_sel_hi:[1,0]
	v_pk_mul_f32 v[216:217], v[216:217], v[210:211] op_sel_hi:[1,0]
	v_pk_mul_f32 v[218:219], v[218:219], v[210:211] op_sel_hi:[1,0]
	v_pk_mul_f32 v[212:213], v[212:213], v[210:211] op_sel_hi:[1,0]
	v_pk_mul_f32 v[214:215], v[214:215], v[210:211] op_sel_hi:[1,0]
	v_pk_mul_f32 v[208:209], v[208:209], v[210:211] op_sel_hi:[1,0]
	v_pk_mul_f32 v[206:207], v[206:207], v[210:211] op_sel_hi:[1,0]
	v_pk_mul_f32 v[200:201], v[112:113], v[220:221]
	v_pk_mul_f32 v[202:203], v[114:115], v[222:223]
	v_pk_mul_f32 v[218:219], v[118:119], v[218:219]
	v_pk_mul_f32 v[216:217], v[116:117], v[216:217]
	s_waitcnt vmcnt(0)
; __device__ __forceinline__ unsigned pk_bf16(float lo, float hi) { f32x2 v = {lo, hi}; bf16x2_t b = __builtin_convertvector(v, bf16x2_t); return __builtin_bit_cast(unsigned, b); }
;     __device__ __forceinline__ void operator()(const f32x4 (&acc)[2][2][4][2], const Unit& u, int wr, int wc, int fr, int fq) const {
;     ...
;             for (int ai = 0; ai < 2; ++ai)
; #pragma unroll
;                 for (int m = 0; m < 4; ++m) {
;                     const int row = row0 + ai * HALF + m * 16; const int t = row & 16383;
;                     const float rv = rsqrtf(rowss[row] * (1.0f / 1024.0f) + 1e-6f);
;                     float ss = 0.f; f32x4 hv[2][2];
; #pragma unroll
;                     for (int bj = 0; bj < 2; ++bj)
; #pragma unroll
;                         for (int n = 0; n < 2; ++n) { const f32x4 v = acc[ai][bj][m][n] * rv + *(const f32x4*)(bp + bj * HALF + 4 * n); hv[bj][n] = v; ss += (v[0] * v[0] + v[1] * v[1]) + (v[2] * v[2] + v[3] * v[3]); }
;                     ss += __shfl_xor(ss, 16); ss += __shfl_xor(ss, 32);
;                     const float rinv = rsqrtf(ss * (1.0f / 64.0f) + 1e-6f) * osc;
; #pragma unroll
;                     for (int bj = 0; bj < 2; ++bj) {
;                         const int pos = bj == 0 ? (t >> 6) : (t & 63);
;                         const f32x4 c = *(const f32x4*)(ropec + pos * 16 + 4 * fqo), s = *(const f32x4*)(ropes + pos * 16 + 4 * fqo);
;                         const f32x4 x1 = hv[bj][0] * rinv * *(const f32x4*)(gw + 32 * bj), x2 = hv[bj][1] * rinv * *(const f32x4*)(gw + 32 * bj + 16);
;                         const f32x4 o1 = x1 * c - x2 * s, o2 = x2 * c + x1 * s;
;                         u32x4 w; w.x = pk_bf16(o1[0], o1[1]); w.y = pk_bf16(o1[2], o1[3]); w.z = pk_bf16(o2[0], o2[1]); w.w = pk_bf16(o2[2], o2[3]);
;                         *(u32x4*)(base + (size_t)row * pitch + 32 * bj) = w;
;                     }
	v_pk_mul_f32 v[222:223], v[132:133], v[218:219]
	v_pk_mul_f32 v[220:221], v[130:131], v[216:217]
	v_pk_fma_f32 v[222:223], v[136:137], v[202:203], v[222:223] neg_lo:[0,0,1] neg_hi:[0,0,1]
	v_pk_fma_f32 v[220:221], v[134:135], v[200:201], v[220:221] neg_lo:[0,0,1] neg_hi:[0,0,1]
	v_pk_mul_f32 v[134:135], v[134:135], v[216:217]
	v_pk_mul_f32 v[136:137], v[136:137], v[218:219]
	s_nop 0
	v_pk_fma_f32 v[136:137], v[132:133], v[202:203], v[136:137]
	v_pk_fma_f32 v[132:133], v[130:131], v[200:201], v[134:135]
	v_cvt_pk_bf16_f32 v130, v220, v221
	v_cvt_pk_bf16_f32 v131, v222, v223
	v_cvt_pk_bf16_f32 v132, v132, v133
	v_cvt_pk_bf16_f32 v133, v136, v137
	global_store_dwordx4 v[204:205], v[130:133], off
	v_lshl_add_u64 v[200:201], v[138:139], 0, v[160:161]
	v_lshl_add_u64 v[202:203], v[140:141], 0, v[160:161]
	global_load_dwordx4 v[130:133], v[200:201], off
	global_load_dwordx4 v[134:137], v[202:203], off
	v_pk_mul_f32 v[214:215], v[48:49], v[214:215]
	v_pk_mul_f32 v[212:213], v[50:51], v[212:213]
	v_pk_mul_f32 v[140:141], v[54:55], v[206:207]
	v_pk_mul_f32 v[138:139], v[52:53], v[208:209]
	s_waitcnt vmcnt(0)
	v_pk_mul_f32 v[208:209], v[136:137], v[140:141]
	v_pk_mul_f32 v[206:207], v[134:135], v[138:139]
	v_pk_fma_f32 v[208:209], v[132:133], v[212:213], v[208:209] neg_lo:[0,0,1] neg_hi:[0,0,1]
	v_pk_fma_f32 v[206:207], v[130:131], v[214:215], v[206:207] neg_lo:[0,0,1] neg_hi:[0,0,1]
	v_pk_mul_f32 v[130:131], v[130:131], v[138:139]
	v_pk_mul_f32 v[132:133], v[132:133], v[140:141]
	s_nop 0
	v_pk_fma_f32 v[136:137], v[136:137], v[212:213], v[132:133]
	v_pk_fma_f32 v[132:133], v[134:135], v[214:215], v[130:131]
	v_cvt_pk_bf16_f32 v130, v206, v207
	v_cvt_pk_bf16_f32 v131, v208, v209
	v_cvt_pk_bf16_f32 v132, v132, v133
	v_cvt_pk_bf16_f32 v133, v136, v137
	global_store_dwordx4 v[204:205], v[130:133], off offset:64
	s_nop 1
	v_fmamk_f32 v130, v251, 0x3a800000, v227
	s_nop 0
	v_rsq_f32_e32 v130, v130
	s_nop 0
	v_mov_b32_e32 v204, v130
	v_pk_fma_f32 v[140:141], v[90:91], v[204:205], v[122:123] op_sel_hi:[1,0,1]
	v_pk_fma_f32 v[218:219], v[92:93], v[204:205], v[124:125] op_sel_hi:[1,0,1]
	v_pk_fma_f32 v[220:221], v[94:95], v[204:205], v[126:127] op_sel_hi:[1,0,1]
	v_pk_mul_f32 v[136:137], v[218:219], v[218:219]
	v_pk_mul_f32 v[134:135], v[220:221], v[220:221]
	s_nop 0
	v_pk_mov_b32 v[138:139], v[136:137], v[134:135] op_sel:[1,0]
	v_mov_b32_e32 v137, v135
	v_pk_add_f32 v[134:135], v[138:139], v[136:137]
	v_pk_fma_f32 v[138:139], v[88:89], v[204:205], v[120:121] op_sel_hi:[1,0,1]
	v_pk_mul_f32 v[130:131], v[140:141], v[140:141]
	v_pk_mul_f32 v[132:133], v[138:139], v[138:139]
	v_pk_add_f32 v[206:207], v[134:135], v[134:135] op_sel_hi:[0,1]
	v_pk_mov_b32 v[134:135], v[132:133], v[130:131] op_sel:[1,0]
	v_mov_b32_e32 v133, v131
	v_pk_add_f32 v[130:131], v[134:135], v[132:133]
	s_nop 0
	v_pk_add_f32 v[216:217], v[130:131], v[130:131] op_sel_hi:[0,1]
	v_pk_fma_f32 v[208:209], v[26:27], v[204:205], v[58:59] op_sel_hi:[1,0,1]
	v_pk_fma_f32 v[214:215], v[28:29], v[204:205], v[60:61] op_sel_hi:[1,0,1]
	v_pk_fma_f32 v[212:213], v[30:31], v[204:205], v[62:63] op_sel_hi:[1,0,1]
	v_mul_f32_e32 v134, v214, v214
	v_pk_fma_f32 v[134:135], v[214:215], v[214:215], v[134:135] op_sel_hi:[1,1,0]
	v_pk_fma_f32 v[210:211], v[24:25], v[204:205], v[56:57] op_sel_hi:[1,0,1]
	v_mul_f32_e32 v134, v212, v212
	v_pk_fma_f32 v[136:137], v[212:213], v[212:213], v[134:135] op_sel_hi:[1,1,0]
	v_mul_f32_e32 v134, v210, v210
	v_mul_f32_e32 v136, v211, v211
	v_mul_f32_e32 v206, v208, v208
	v_mul_f32_e32 v216, v209, v209
	v_pk_add_f32 v[130:131], v[134:135], v[136:137]
	v_pk_add_f32 v[132:133], v[206:207], v[216:217]
	s_nop 0
	v_pk_add_f32 v[130:131], v[130:131], v[132:133]
	s_nop 0
	v_add_f32_e32 v130, v130, v131
	ds_bpermute_b32 v131, v246, v130
	s_waitcnt lgkmcnt(0)
	v_add_f32_e32 v130, v130, v131
	ds_bpermute_b32 v131, v247, v130
	s_waitcnt lgkmcnt(0)
	v_add_f32_e32 v130, v130, v131
	v_fmamk_f32 v130, v130, 0x3c800000, v227
	s_nop 0
	v_rsq_f32_e32 v130, v130
	s_nop 0
	v_mul_f32_e32 v216, v245, v130
	v_pk_mul_f32 v[222:223], v[220:221], v[216:217] op_sel_hi:[1,0]
	v_pk_mul_f32 v[224:225], v[218:219], v[216:217] op_sel_hi:[1,0]
	v_mad_i64_i32 v[130:131], s[4:5], s0, v159, 0
	v_lshl_add_u64 v[206:207], v[130:131], 1, v[170:171]
	v_and_b32_e32 v130, 0x3fc0, v159
	v_mov_b32_e32 v131, v129
	v_lshl_add_u64 v[132:133], s[82:83], 0, v[130:131]
	v_lshl_add_u64 v[130:131], s[84:85], 0, v[130:131]
	v_lshl_add_u64 v[204:205], v[132:133], 0, v[186:187]
	v_lshl_add_u64 v[186:187], v[130:131], 0, v[186:187]
	global_load_dwordx4 v[134:137], v[204:205], off
	global_load_dwordx4 v[130:133], v[186:187], off
	v_pk_mul_f32 v[210:211], v[210:211], v[216:217] op_sel_hi:[1,0]
	v_pk_mul_f32 v[208:209], v[208:209], v[216:217] op_sel_hi:[1,0]
	v_add_u32_e32 v159, 0x90, v162
	v_pk_mul_f32 v[218:219], v[112:113], v[224:225]
	v_pk_mul_f32 v[220:221], v[114:115], v[222:223]
	v_pk_mul_f32 v[222:223], v[138:139], v[216:217] op_sel_hi:[1,0]
	v_pk_mul_f32 v[224:225], v[140:141], v[216:217] op_sel_hi:[1,0]
	v_pk_mul_f32 v[140:141], v[118:119], v[224:225]
	v_pk_mul_f32 v[138:139], v[116:117], v[222:223]
	s_waitcnt vmcnt(0)
; __device__ __forceinline__ unsigned pk_bf16(float lo, float hi) { f32x2 v = {lo, hi}; bf16x2_t b = __builtin_convertvector(v, bf16x2_t); return __builtin_bit_cast(unsigned, b); }
;     __device__ __forceinline__ void operator()(const f32x4 (&acc)[2][2][4][2], const Unit& u, int wr, int wc, int fr, int fq) const {
;     ...
;             for (int ai = 0; ai < 2; ++ai)
; #pragma unroll
;                 for (int m = 0; m < 4; ++m) {
;                     const int row = row0 + ai * HALF + m * 16; const int t = row & 16383;
;                     const float rv = rsqrtf(rowss[row] * (1.0f / 1024.0f) + 1e-6f);
;                     float ss = 0.f; f32x4 hv[2][2];
; #pragma unroll
;                     for (int bj = 0; bj < 2; ++bj)
; #pragma unroll
;                         for (int n = 0; n < 2; ++n) { const f32x4 v = acc[ai][bj][m][n] * rv + *(const f32x4*)(bp + bj * HALF + 4 * n); hv[bj][n] = v; ss += (v[0] * v[0] + v[1] * v[1]) + (v[2] * v[2] + v[3] * v[3]); }
;                     ss += __shfl_xor(ss, 16); ss += __shfl_xor(ss, 32);
;                     const float rinv = rsqrtf(ss * (1.0f / 64.0f) + 1e-6f) * osc;
; #pragma unroll
;                     for (int bj = 0; bj < 2; ++bj) {
;                         const int pos = bj == 0 ? (t >> 6) : (t & 63);
;                         const f32x4 c = *(const f32x4*)(ropec + pos * 16 + 4 * fqo), s = *(const f32x4*)(ropes + pos * 16 + 4 * fqo);
;                         const f32x4 x1 = hv[bj][0] * rinv * *(const f32x4*)(gw + 32 * bj), x2 = hv[bj][1] * rinv * *(const f32x4*)(gw + 32 * bj + 16);
;                         const f32x4 o1 = x1 * c - x2 * s, o2 = x2 * c + x1 * s;
;                         u32x4 w; w.x = pk_bf16(o1[0], o1[1]); w.y = pk_bf16(o1[2], o1[3]); w.z = pk_bf16(o2[0], o2[1]); w.w = pk_bf16(o2[2], o2[3]);
;                         *(u32x4*)(base + (size_t)row * pitch + 32 * bj) = w;
;                     }
	v_pk_mul_f32 v[224:225], v[132:133], v[140:141]
	v_pk_mul_f32 v[222:223], v[130:131], v[138:139]
	v_pk_fma_f32 v[224:225], v[136:137], v[220:221], v[224:225] neg_lo:[0,0,1] neg_hi:[0,0,1]
	v_pk_fma_f32 v[222:223], v[134:135], v[218:219], v[222:223] neg_lo:[0,0,1] neg_hi:[0,0,1]
	v_pk_mul_f32 v[134:135], v[134:135], v[138:139]
	v_pk_mul_f32 v[136:137], v[136:137], v[140:141]
	s_nop 0
	v_pk_fma_f32 v[136:137], v[132:133], v[220:221], v[136:137]
	v_pk_fma_f32 v[132:133], v[130:131], v[218:219], v[134:135]
	v_cvt_pk_bf16_f32 v130, v222, v223
	v_cvt_pk_bf16_f32 v131, v224, v225
	v_cvt_pk_bf16_f32 v132, v132, v133
	v_cvt_pk_bf16_f32 v133, v136, v137
	global_store_dwordx4 v[206:207], v[130:133], off
	global_load_dwordx4 v[130:133], v[192:193], off
	s_nop 0
	global_load_dwordx4 v[134:137], v[194:195], off
	v_pk_mul_f32 v[192:193], v[212:213], v[216:217] op_sel_hi:[1,0]
	v_pk_mul_f32 v[194:195], v[214:215], v[216:217] op_sel_hi:[1,0]
	v_pk_mul_f32 v[192:193], v[50:51], v[192:193]
	v_pk_mul_f32 v[194:195], v[48:49], v[194:195]
	v_pk_mul_f32 v[140:141], v[54:55], v[208:209]
	v_pk_mul_f32 v[138:139], v[52:53], v[210:211]
	s_waitcnt vmcnt(0)
	v_pk_mul_f32 v[210:211], v[136:137], v[140:141]
	v_pk_mul_f32 v[208:209], v[134:135], v[138:139]
	v_pk_fma_f32 v[210:211], v[132:133], v[192:193], v[210:211] neg_lo:[0,0,1] neg_hi:[0,0,1]
	v_pk_fma_f32 v[208:209], v[130:131], v[194:195], v[208:209] neg_lo:[0,0,1] neg_hi:[0,0,1]
	v_pk_mul_f32 v[130:131], v[130:131], v[138:139]
	v_pk_mul_f32 v[132:133], v[132:133], v[140:141]
	s_nop 0
	v_pk_fma_f32 v[136:137], v[136:137], v[192:193], v[132:133]
	v_pk_fma_f32 v[132:133], v[134:135], v[194:195], v[130:131]
	v_cvt_pk_bf16_f32 v130, v208, v209
	v_cvt_pk_bf16_f32 v131, v210, v211
	v_cvt_pk_bf16_f32 v132, v132, v133
	v_cvt_pk_bf16_f32 v133, v136, v137
	global_store_dwordx4 v[206:207], v[130:133], off offset:64
	s_nop 1
	v_fmamk_f32 v130, v143, 0x3a800000, v227
	s_nop 0
	v_rsq_f32_e32 v130, v130
	s_nop 0
	v_mov_b32_e32 v192, v130
	v_pk_fma_f32 v[140:141], v[82:83], v[192:193], v[122:123] op_sel_hi:[1,0,1]
	v_pk_fma_f32 v[214:215], v[84:85], v[192:193], v[124:125] op_sel_hi:[1,0,1]
	v_pk_fma_f32 v[216:217], v[86:87], v[192:193], v[126:127] op_sel_hi:[1,0,1]
	v_pk_mul_f32 v[136:137], v[214:215], v[214:215]
	v_pk_mul_f32 v[134:135], v[216:217], v[216:217]
	s_nop 0
	v_pk_mov_b32 v[138:139], v[136:137], v[134:135] op_sel:[1,0]
	v_mov_b32_e32 v137, v135
	v_pk_add_f32 v[134:135], v[138:139], v[136:137]
	v_pk_fma_f32 v[138:139], v[80:81], v[192:193], v[120:121] op_sel_hi:[1,0,1]
	v_pk_mul_f32 v[130:131], v[140:141], v[140:141]
	v_pk_mul_f32 v[132:133], v[138:139], v[138:139]
	v_pk_add_f32 v[212:213], v[134:135], v[134:135] op_sel_hi:[0,1]
	v_pk_mov_b32 v[134:135], v[132:133], v[130:131] op_sel:[1,0]
	v_mov_b32_e32 v133, v131
	v_pk_add_f32 v[130:131], v[134:135], v[132:133]
	s_nop 0
	v_pk_add_f32 v[218:219], v[130:131], v[130:131] op_sel_hi:[0,1]
	v_pk_fma_f32 v[194:195], v[18:19], v[192:193], v[58:59] op_sel_hi:[1,0,1]
	v_pk_fma_f32 v[210:211], v[20:21], v[192:193], v[60:61] op_sel_hi:[1,0,1]
	v_pk_fma_f32 v[208:209], v[22:23], v[192:193], v[62:63] op_sel_hi:[1,0,1]
	v_mul_f32_e32 v134, v210, v210
	v_pk_fma_f32 v[134:135], v[210:211], v[210:211], v[134:135] op_sel_hi:[1,1,0]
	v_pk_fma_f32 v[206:207], v[16:17], v[192:193], v[56:57] op_sel_hi:[1,0,1]
	v_mul_f32_e32 v134, v208, v208
	v_pk_fma_f32 v[136:137], v[208:209], v[208:209], v[134:135] op_sel_hi:[1,1,0]
	v_mul_f32_e32 v134, v206, v206
	v_mul_f32_e32 v136, v207, v207
	v_mul_f32_e32 v212, v194, v194
	v_mul_f32_e32 v218, v195, v195
	v_pk_add_f32 v[130:131], v[134:135], v[136:137]
	v_pk_add_f32 v[132:133], v[212:213], v[218:219]
	s_nop 0
	v_pk_add_f32 v[130:131], v[130:131], v[132:133]
	s_nop 0
	v_add_f32_e32 v130, v130, v131
	ds_bpermute_b32 v131, v246, v130
	s_waitcnt lgkmcnt(0)
	v_add_f32_e32 v130, v130, v131
	ds_bpermute_b32 v131, v247, v130
	s_waitcnt lgkmcnt(0)
	v_add_f32_e32 v130, v130, v131
	v_fmamk_f32 v130, v130, 0x3c800000, v227
	s_nop 0
	v_rsq_f32_e32 v130, v130
	s_nop 0
	v_mul_f32_e32 v212, v245, v130
	v_mad_i64_i32 v[130:131], s[4:5], s0, v159, 0
	v_lshl_add_u64 v[192:193], v[130:131], 1, v[170:171]
	global_load_dwordx4 v[134:137], v[204:205], off
	global_load_dwordx4 v[130:133], v[186:187], off
	v_pk_mul_f32 v[218:219], v[216:217], v[212:213] op_sel_hi:[1,0]
	v_pk_mul_f32 v[220:221], v[214:215], v[212:213] op_sel_hi:[1,0]
	v_pk_mul_f32 v[206:207], v[206:207], v[212:213] op_sel_hi:[1,0]
	v_pk_mul_f32 v[194:195], v[194:195], v[212:213] op_sel_hi:[1,0]
	v_add_u32_e32 v159, 0xa0, v162
	v_pk_mul_f32 v[214:215], v[112:113], v[220:221]
	v_pk_mul_f32 v[216:217], v[114:115], v[218:219]
	v_pk_mul_f32 v[218:219], v[138:139], v[212:213] op_sel_hi:[1,0]
	v_pk_mul_f32 v[220:221], v[140:141], v[212:213] op_sel_hi:[1,0]
	v_pk_mul_f32 v[140:141], v[118:119], v[220:221]
	v_pk_mul_f32 v[138:139], v[116:117], v[218:219]
	s_waitcnt vmcnt(0)
	v_pk_mul_f32 v[220:221], v[132:133], v[140:141]
	v_pk_mul_f32 v[218:219], v[130:131], v[138:139]
	v_pk_fma_f32 v[220:221], v[136:137], v[216:217], v[220:221] neg_lo:[0,0,1] neg_hi:[0,0,1]
	v_pk_fma_f32 v[218:219], v[134:135], v[214:215], v[218:219] neg_lo:[0,0,1] neg_hi:[0,0,1]
	v_pk_mul_f32 v[134:135], v[134:135], v[138:139]
	v_pk_mul_f32 v[136:137], v[136:137], v[140:141]
	s_nop 0
	v_pk_fma_f32 v[136:137], v[132:133], v[216:217], v[136:137]
	v_pk_fma_f32 v[132:133], v[130:131], v[214:215], v[134:135]
	v_cvt_pk_bf16_f32 v130, v218, v219
	v_cvt_pk_bf16_f32 v131, v220, v221
	v_cvt_pk_bf16_f32 v132, v132, v133
	v_cvt_pk_bf16_f32 v133, v136, v137
	global_store_dwordx4 v[192:193], v[130:133], off
	global_load_dwordx4 v[130:133], v[188:189], off
	s_nop 0
	global_load_dwordx4 v[134:137], v[190:191], off
	v_pk_mul_f32 v[188:189], v[208:209], v[212:213] op_sel_hi:[1,0]
	v_pk_mul_f32 v[190:191], v[210:211], v[212:213] op_sel_hi:[1,0]
	v_pk_mul_f32 v[188:189], v[50:51], v[188:189]
	v_pk_mul_f32 v[190:191], v[48:49], v[190:191]
	v_pk_mul_f32 v[140:141], v[54:55], v[194:195]
	v_pk_mul_f32 v[138:139], v[52:53], v[206:207]
	s_waitcnt vmcnt(0)
; __device__ __forceinline__ unsigned pk_bf16(float lo, float hi) { f32x2 v = {lo, hi}; bf16x2_t b = __builtin_convertvector(v, bf16x2_t); return __builtin_bit_cast(unsigned, b); }
;     __device__ __forceinline__ void operator()(const f32x4 (&acc)[2][2][4][2], const Unit& u, int wr, int wc, int fr, int fq) const {
;     ...
;             for (int ai = 0; ai < 2; ++ai)
; #pragma unroll
;                 for (int m = 0; m < 4; ++m) {
;                     const int row = row0 + ai * HALF + m * 16; const int t = row & 16383;
;                     const float rv = rsqrtf(rowss[row] * (1.0f / 1024.0f) + 1e-6f);
;                     float ss = 0.f; f32x4 hv[2][2];
; #pragma unroll
;                     for (int bj = 0; bj < 2; ++bj)
; #pragma unroll
;                         for (int n = 0; n < 2; ++n) { const f32x4 v = acc[ai][bj][m][n] * rv + *(const f32x4*)(bp + bj * HALF + 4 * n); hv[bj][n] = v; ss += (v[0] * v[0] + v[1] * v[1]) + (v[2] * v[2] + v[3] * v[3]); }
;                     ss += __shfl_xor(ss, 16); ss += __shfl_xor(ss, 32);
;                     const float rinv = rsqrtf(ss * (1.0f / 64.0f) + 1e-6f) * osc;
; #pragma unroll
;                     for (int bj = 0; bj < 2; ++bj) {
;                         const int pos = bj == 0 ? (t >> 6) : (t & 63);
;                         const f32x4 c = *(const f32x4*)(ropec + pos * 16 + 4 * fqo), s = *(const f32x4*)(ropes + pos * 16 + 4 * fqo);
;                         const f32x4 x1 = hv[bj][0] * rinv * *(const f32x4*)(gw + 32 * bj), x2 = hv[bj][1] * rinv * *(const f32x4*)(gw + 32 * bj + 16);
;                         const f32x4 o1 = x1 * c - x2 * s, o2 = x2 * c + x1 * s;
;                         u32x4 w; w.x = pk_bf16(o1[0], o1[1]); w.y = pk_bf16(o1[2], o1[3]); w.z = pk_bf16(o2[0], o2[1]); w.w = pk_bf16(o2[2], o2[3]);
;                         *(u32x4*)(base + (size_t)row * pitch + 32 * bj) = w;
;                     }
	v_pk_mul_f32 v[206:207], v[136:137], v[140:141]
	v_pk_mul_f32 v[194:195], v[134:135], v[138:139]
	v_pk_fma_f32 v[206:207], v[132:133], v[188:189], v[206:207] neg_lo:[0,0,1] neg_hi:[0,0,1]
	v_pk_fma_f32 v[194:195], v[130:131], v[190:191], v[194:195] neg_lo:[0,0,1] neg_hi:[0,0,1]
	v_pk_mul_f32 v[130:131], v[130:131], v[138:139]
	v_pk_mul_f32 v[132:133], v[132:133], v[140:141]
	s_nop 0
	v_pk_fma_f32 v[136:137], v[136:137], v[188:189], v[132:133]
	v_pk_fma_f32 v[132:133], v[134:135], v[190:191], v[130:131]
	v_cvt_pk_bf16_f32 v130, v194, v195
	v_cvt_pk_bf16_f32 v131, v206, v207
	v_cvt_pk_bf16_f32 v132, v132, v133
	v_cvt_pk_bf16_f32 v133, v136, v137
	global_store_dwordx4 v[192:193], v[130:133], off offset:64
	s_nop 1
	v_fmamk_f32 v130, v145, 0x3a800000, v227
	s_nop 0
	v_rsq_f32_e32 v130, v130
	s_nop 0
	v_mov_b32_e32 v188, v130
	v_pk_fma_f32 v[140:141], v[74:75], v[188:189], v[122:123] op_sel_hi:[1,0,1]
	v_pk_fma_f32 v[210:211], v[76:77], v[188:189], v[124:125] op_sel_hi:[1,0,1]
	v_pk_fma_f32 v[212:213], v[78:79], v[188:189], v[126:127] op_sel_hi:[1,0,1]
	v_pk_mul_f32 v[136:137], v[210:211], v[210:211]
	v_pk_mul_f32 v[134:135], v[212:213], v[212:213]
	s_nop 0
	v_pk_mov_b32 v[138:139], v[136:137], v[134:135] op_sel:[1,0]
	v_mov_b32_e32 v137, v135
	v_pk_add_f32 v[134:135], v[138:139], v[136:137]
	v_pk_fma_f32 v[138:139], v[72:73], v[188:189], v[120:121] op_sel_hi:[1,0,1]
	v_pk_mul_f32 v[130:131], v[140:141], v[140:141]
	v_pk_mul_f32 v[132:133], v[138:139], v[138:139]
	v_pk_add_f32 v[208:209], v[134:135], v[134:135] op_sel_hi:[0,1]
	v_pk_mov_b32 v[134:135], v[132:133], v[130:131] op_sel:[1,0]
	v_mov_b32_e32 v133, v131
	v_pk_add_f32 v[130:131], v[134:135], v[132:133]
	s_nop 0
	v_pk_add_f32 v[214:215], v[130:131], v[130:131] op_sel_hi:[0,1]
	v_pk_fma_f32 v[190:191], v[10:11], v[188:189], v[58:59] op_sel_hi:[1,0,1]
	v_pk_fma_f32 v[206:207], v[12:13], v[188:189], v[60:61] op_sel_hi:[1,0,1]
	v_pk_fma_f32 v[194:195], v[14:15], v[188:189], v[62:63] op_sel_hi:[1,0,1]
	v_mul_f32_e32 v134, v206, v206
	v_pk_fma_f32 v[134:135], v[206:207], v[206:207], v[134:135] op_sel_hi:[1,1,0]
	v_pk_fma_f32 v[192:193], v[8:9], v[188:189], v[56:57] op_sel_hi:[1,0,1]
	v_mul_f32_e32 v134, v194, v194
	v_pk_fma_f32 v[136:137], v[194:195], v[194:195], v[134:135] op_sel_hi:[1,1,0]
	v_mul_f32_e32 v134, v192, v192
	v_mul_f32_e32 v136, v193, v193
	v_mul_f32_e32 v208, v190, v190
	v_mul_f32_e32 v214, v191, v191
	v_pk_add_f32 v[130:131], v[134:135], v[136:137]
	v_pk_add_f32 v[132:133], v[208:209], v[214:215]
	s_nop 0
	v_pk_add_f32 v[130:131], v[130:131], v[132:133]
	s_nop 0
	v_add_f32_e32 v130, v130, v131
	ds_bpermute_b32 v131, v246, v130
	s_waitcnt lgkmcnt(0)
	v_add_f32_e32 v130, v130, v131
	ds_bpermute_b32 v131, v247, v130
	s_waitcnt lgkmcnt(0)
	v_add_f32_e32 v130, v130, v131
	v_fmamk_f32 v130, v130, 0x3c800000, v227
	s_nop 0
	v_rsq_f32_e32 v130, v130
	s_nop 0
	v_mul_f32_e32 v208, v245, v130
	v_mad_i64_i32 v[130:131], s[4:5], s0, v159, 0
	v_lshl_add_u64 v[188:189], v[130:131], 1, v[170:171]
	global_load_dwordx4 v[134:137], v[204:205], off
	global_load_dwordx4 v[130:133], v[186:187], off
	v_pk_mul_f32 v[214:215], v[212:213], v[208:209] op_sel_hi:[1,0]
	v_pk_mul_f32 v[216:217], v[210:211], v[208:209] op_sel_hi:[1,0]
	v_pk_mul_f32 v[194:195], v[194:195], v[208:209] op_sel_hi:[1,0]
	v_pk_mul_f32 v[192:193], v[192:193], v[208:209] op_sel_hi:[1,0]
	v_pk_mul_f32 v[190:191], v[190:191], v[208:209] op_sel_hi:[1,0]
	v_add_u32_e32 v159, 0xb0, v162
	v_pk_mul_f32 v[210:211], v[112:113], v[216:217]
	v_pk_mul_f32 v[212:213], v[114:115], v[214:215]
	v_pk_mul_f32 v[214:215], v[138:139], v[208:209] op_sel_hi:[1,0]
	v_pk_mul_f32 v[216:217], v[140:141], v[208:209] op_sel_hi:[1,0]
	v_pk_mul_f32 v[140:141], v[118:119], v[216:217]
	v_pk_mul_f32 v[138:139], v[116:117], v[214:215]
	s_waitcnt vmcnt(0)
	v_pk_mul_f32 v[216:217], v[132:133], v[140:141]
	v_pk_mul_f32 v[214:215], v[130:131], v[138:139]
	v_pk_fma_f32 v[216:217], v[136:137], v[212:213], v[216:217] neg_lo:[0,0,1] neg_hi:[0,0,1]
	v_pk_fma_f32 v[214:215], v[134:135], v[210:211], v[214:215] neg_lo:[0,0,1] neg_hi:[0,0,1]
	v_pk_mul_f32 v[134:135], v[134:135], v[138:139]
	v_pk_mul_f32 v[136:137], v[136:137], v[140:141]
	s_nop 0
	v_pk_fma_f32 v[136:137], v[132:133], v[212:213], v[136:137]
	v_pk_fma_f32 v[132:133], v[130:131], v[210:211], v[134:135]
	v_cvt_pk_bf16_f32 v130, v214, v215
	v_cvt_pk_bf16_f32 v131, v216, v217
	v_cvt_pk_bf16_f32 v132, v132, v133
	v_cvt_pk_bf16_f32 v133, v136, v137
	global_store_dwordx4 v[188:189], v[130:133], off
	global_load_dwordx4 v[130:133], v[196:197], off
	s_nop 0
	global_load_dwordx4 v[134:137], v[198:199], off
	v_pk_mul_f32 v[196:197], v[206:207], v[208:209] op_sel_hi:[1,0]
	v_pk_mul_f32 v[194:195], v[50:51], v[194:195]
	v_pk_mul_f32 v[196:197], v[48:49], v[196:197]
	v_pk_mul_f32 v[140:141], v[54:55], v[190:191]
	v_pk_mul_f32 v[138:139], v[52:53], v[192:193]
	s_waitcnt vmcnt(0)
; __device__ __forceinline__ unsigned pk_bf16(float lo, float hi) { f32x2 v = {lo, hi}; bf16x2_t b = __builtin_convertvector(v, bf16x2_t); return __builtin_bit_cast(unsigned, b); }
;     __device__ __forceinline__ void operator()(const f32x4 (&acc)[2][2][4][2], const Unit& u, int wr, int wc, int fr, int fq) const {
;     ...
;             for (int ai = 0; ai < 2; ++ai)
; #pragma unroll
;                 for (int m = 0; m < 4; ++m) {
;                     const int row = row0 + ai * HALF + m * 16; const int t = row & 16383;
;                     const float rv = rsqrtf(rowss[row] * (1.0f / 1024.0f) + 1e-6f);
;                     float ss = 0.f; f32x4 hv[2][2];
; #pragma unroll
;                     for (int bj = 0; bj < 2; ++bj)
; #pragma unroll
;                         for (int n = 0; n < 2; ++n) { const f32x4 v = acc[ai][bj][m][n] * rv + *(const f32x4*)(bp + bj * HALF + 4 * n); hv[bj][n] = v; ss += (v[0] * v[0] + v[1] * v[1]) + (v[2] * v[2] + v[3] * v[3]); }
;                     ss += __shfl_xor(ss, 16); ss += __shfl_xor(ss, 32);
;                     const float rinv = rsqrtf(ss * (1.0f / 64.0f) + 1e-6f) * osc;
; #pragma unroll
;                     for (int bj = 0; bj < 2; ++bj) {
;                         const int pos = bj == 0 ? (t >> 6) : (t & 63);
;                         const f32x4 c = *(const f32x4*)(ropec + pos * 16 + 4 * fqo), s = *(const f32x4*)(ropes + pos * 16 + 4 * fqo);
;                         const f32x4 x1 = hv[bj][0] * rinv * *(const f32x4*)(gw + 32 * bj), x2 = hv[bj][1] * rinv * *(const f32x4*)(gw + 32 * bj + 16);
;                         const f32x4 o1 = x1 * c - x2 * s, o2 = x2 * c + x1 * s;
;                         u32x4 w; w.x = pk_bf16(o1[0], o1[1]); w.y = pk_bf16(o1[2], o1[3]); w.z = pk_bf16(o2[0], o2[1]); w.w = pk_bf16(o2[2], o2[3]);
;                         *(u32x4*)(base + (size_t)row * pitch + 32 * bj) = w;
;                     }
	v_pk_mul_f32 v[192:193], v[136:137], v[140:141]
	v_pk_mul_f32 v[190:191], v[134:135], v[138:139]
	v_pk_fma_f32 v[192:193], v[132:133], v[194:195], v[192:193] neg_lo:[0,0,1] neg_hi:[0,0,1]
	v_pk_fma_f32 v[190:191], v[130:131], v[196:197], v[190:191] neg_lo:[0,0,1] neg_hi:[0,0,1]
	v_pk_mul_f32 v[130:131], v[130:131], v[138:139]
	v_pk_mul_f32 v[132:133], v[132:133], v[140:141]
	s_nop 0
	v_pk_fma_f32 v[136:137], v[136:137], v[194:195], v[132:133]
	v_pk_fma_f32 v[132:133], v[134:135], v[196:197], v[130:131]
	v_cvt_pk_bf16_f32 v130, v190, v191
	v_cvt_pk_bf16_f32 v131, v192, v193
	v_cvt_pk_bf16_f32 v132, v132, v133
	v_cvt_pk_bf16_f32 v133, v136, v137
	global_store_dwordx4 v[188:189], v[130:133], off offset:64
	s_nop 1
	v_fmamk_f32 v130, v147, 0x3a800000, v227
	s_nop 0
	v_rsq_f32_e32 v130, v130
	s_nop 0
	v_mov_b32_e32 v188, v130
	v_pk_fma_f32 v[140:141], v[66:67], v[188:189], v[122:123] op_sel_hi:[1,0,1]
	v_pk_fma_f32 v[196:197], v[68:69], v[188:189], v[124:125] op_sel_hi:[1,0,1]
	v_pk_fma_f32 v[198:199], v[70:71], v[188:189], v[126:127] op_sel_hi:[1,0,1]
	v_pk_mul_f32 v[136:137], v[196:197], v[196:197]
	v_pk_mul_f32 v[134:135], v[198:199], v[198:199]
	s_nop 0
	v_pk_mov_b32 v[138:139], v[136:137], v[134:135] op_sel:[1,0]
	v_mov_b32_e32 v137, v135
	v_pk_add_f32 v[134:135], v[138:139], v[136:137]
	v_pk_fma_f32 v[138:139], v[64:65], v[188:189], v[120:121] op_sel_hi:[1,0,1]
	v_pk_mul_f32 v[130:131], v[140:141], v[140:141]
	v_pk_mul_f32 v[132:133], v[138:139], v[138:139]
	v_pk_add_f32 v[194:195], v[134:135], v[134:135] op_sel_hi:[0,1]
	v_pk_mov_b32 v[134:135], v[132:133], v[130:131] op_sel:[1,0]
	v_mov_b32_e32 v133, v131
	v_pk_add_f32 v[130:131], v[134:135], v[132:133]
	s_nop 0
	v_pk_add_f32 v[206:207], v[130:131], v[130:131] op_sel_hi:[0,1]
	v_pk_fma_f32 v[172:173], v[2:3], v[188:189], v[58:59] op_sel_hi:[1,0,1]
	v_pk_fma_f32 v[192:193], v[4:5], v[188:189], v[60:61] op_sel_hi:[1,0,1]
	v_pk_fma_f32 v[190:191], v[6:7], v[188:189], v[62:63] op_sel_hi:[1,0,1]
	v_mul_f32_e32 v134, v192, v192
	v_pk_fma_f32 v[134:135], v[192:193], v[192:193], v[134:135] op_sel_hi:[1,1,0]
	v_pk_fma_f32 v[188:189], v[0:1], v[188:189], v[56:57] op_sel_hi:[1,0,1]
	v_mul_f32_e32 v134, v190, v190
	v_pk_fma_f32 v[136:137], v[190:191], v[190:191], v[134:135] op_sel_hi:[1,1,0]
	v_mul_f32_e32 v134, v188, v188
	v_mul_f32_e32 v136, v189, v189
	v_mul_f32_e32 v194, v172, v172
	v_mul_f32_e32 v206, v173, v173
	v_pk_add_f32 v[130:131], v[134:135], v[136:137]
	v_pk_add_f32 v[132:133], v[194:195], v[206:207]
	s_nop 0
	v_pk_add_f32 v[130:131], v[130:131], v[132:133]
	s_nop 0
	v_add_f32_e32 v130, v130, v131
	ds_bpermute_b32 v131, v246, v130
	s_waitcnt lgkmcnt(0)
	v_add_f32_e32 v130, v130, v131
	ds_bpermute_b32 v131, v247, v130
	s_waitcnt lgkmcnt(0)
	v_add_f32_e32 v130, v130, v131
	v_fmamk_f32 v130, v130, 0x3c800000, v227
	s_nop 0
	v_rsq_f32_e32 v130, v130
	s_nop 0
	v_mul_f32_e32 v194, v245, v130
	v_mad_i64_i32 v[130:131], s[0:1], s0, v159, 0
	v_lshl_add_u64 v[170:171], v[130:131], 1, v[170:171]
	global_load_dwordx4 v[134:137], v[204:205], off
	global_load_dwordx4 v[130:133], v[186:187], off
	v_pk_mul_f32 v[204:205], v[198:199], v[194:195] op_sel_hi:[1,0]
	v_pk_mul_f32 v[186:187], v[196:197], v[194:195] op_sel_hi:[1,0]
	v_pk_mul_f32 v[188:189], v[188:189], v[194:195] op_sel_hi:[1,0]
	v_pk_mul_f32 v[172:173], v[172:173], v[194:195] op_sel_hi:[1,0]
	s_mov_b64 s[0:1], 0
	v_pk_mul_f32 v[186:187], v[112:113], v[186:187]
	v_pk_mul_f32 v[196:197], v[114:115], v[204:205]
	v_pk_mul_f32 v[198:199], v[138:139], v[194:195] op_sel_hi:[1,0]
	v_pk_mul_f32 v[204:205], v[140:141], v[194:195] op_sel_hi:[1,0]
	v_pk_mul_f32 v[140:141], v[118:119], v[204:205]
	v_pk_mul_f32 v[138:139], v[116:117], v[198:199]
	s_waitcnt vmcnt(0)
	v_pk_mul_f32 v[204:205], v[132:133], v[140:141]
	v_pk_mul_f32 v[198:199], v[130:131], v[138:139]
	v_pk_fma_f32 v[204:205], v[136:137], v[196:197], v[204:205] neg_lo:[0,0,1] neg_hi:[0,0,1]
	v_pk_fma_f32 v[198:199], v[134:135], v[186:187], v[198:199] neg_lo:[0,0,1] neg_hi:[0,0,1]
	v_pk_mul_f32 v[134:135], v[134:135], v[138:139]
	v_pk_mul_f32 v[136:137], v[136:137], v[140:141]
	s_nop 0
	v_pk_fma_f32 v[136:137], v[132:133], v[196:197], v[136:137]
	v_pk_fma_f32 v[132:133], v[130:131], v[186:187], v[134:135]
	v_cvt_pk_bf16_f32 v130, v198, v199
	v_cvt_pk_bf16_f32 v131, v204, v205
	v_cvt_pk_bf16_f32 v132, v132, v133
	v_cvt_pk_bf16_f32 v133, v136, v137
	global_store_dwordx4 v[170:171], v[130:133], off
	global_load_dwordx4 v[130:133], v[200:201], off
	s_nop 0
	global_load_dwordx4 v[134:137], v[202:203], off
	v_pk_mul_f32 v[186:187], v[190:191], v[194:195] op_sel_hi:[1,0]
	v_pk_mul_f32 v[190:191], v[192:193], v[194:195] op_sel_hi:[1,0]
	v_pk_mul_f32 v[186:187], v[50:51], v[186:187]
	v_pk_mul_f32 v[190:191], v[48:49], v[190:191]
	v_pk_mul_f32 v[140:141], v[54:55], v[172:173]
	v_pk_mul_f32 v[138:139], v[52:53], v[188:189]
	s_waitcnt vmcnt(0)
	v_pk_mul_f32 v[172:173], v[136:137], v[140:141]
	v_pk_mul_f32 v[168:169], v[134:135], v[138:139]
	v_pk_fma_f32 v[172:173], v[132:133], v[186:187], v[172:173] neg_lo:[0,0,1] neg_hi:[0,0,1]
	v_pk_fma_f32 v[168:169], v[130:131], v[190:191], v[168:169] neg_lo:[0,0,1] neg_hi:[0,0,1]
	v_pk_mul_f32 v[130:131], v[130:131], v[138:139]
	v_pk_mul_f32 v[132:133], v[132:133], v[140:141]
	s_nop 0
	v_pk_fma_f32 v[136:137], v[136:137], v[186:187], v[132:133]
	v_pk_fma_f32 v[132:133], v[134:135], v[190:191], v[130:131]
	v_cvt_pk_bf16_f32 v130, v168, v169
	v_cvt_pk_bf16_f32 v131, v172, v173
	v_cvt_pk_bf16_f32 v132, v132, v133
	v_cvt_pk_bf16_f32 v133, v136, v137
	global_store_dwordx4 v[170:171], v[130:133], off offset:64
